# layer-0 conv items taken off the 32 workgroups that carry the extra context attention units (bx%8==0), shared by the other 224
# speedup vs baseline: 1.0233x; 1.0063x over previous
.Lconv_entry:
	v_mbcnt_lo_u32_b32 v152, -1, 0
	v_mbcnt_hi_u32_b32 v152, -1, v152
	v_lshl_add_u32 v153, s3, 6, v152
	v_lshlrev_b32_e32 v142, 1, v153
	v_lshlrev_b32_e32 v143, 2, v153
	v_lshrrev_b32_e32 v154, 5, v153
	v_and_b32_e32 v155, 31, v153
	v_lshlrev_b32_e32 v144, 11, v154
	v_lshl_add_u32 v144, v155, 6, v144
	v_lshlrev_b32_e32 v145, 3, v154
	v_add_u32_e32 v145, 0x8000, v145
	v_mov_b32_e32 v151, 0x8000
	v_xor_b32_e32 v146, 1, v152
	v_lshlrev_b32_e32 v146, 2, v146
	v_xor_b32_e32 v147, 2, v152
	v_lshlrev_b32_e32 v147, 2, v147
	v_xor_b32_e32 v148, 4, v152
	v_lshlrev_b32_e32 v148, 2, v148
	v_xor_b32_e32 v149, 8, v152
	v_lshlrev_b32_e32 v149, 2, v149
	v_xor_b32_e32 v150, 16, v152
	v_lshlrev_b32_e32 v150, 2, v150
	s_mov_b32 s72, s55
	v_readlane_b32 s71, v246, 55
	v_readlane_b32 s84, v248, 14
	v_readlane_b32 s85, v248, 15
	v_readlane_b32 s86, v248, 16
	v_readlane_b32 s87, v248, 17
	v_readlane_b32 s90, v248, 18
	v_readlane_b32 s91, v248, 19
	v_readlane_b32 s92, v248, 20
	v_readlane_b32 s93, v248, 21
	s_nop 3
	s_lshr_b32 s71, s71, 4
	s_mov_b32 s70, s2
	s_mov_b32 s97, s34
	s_cmp_lg_u32 s72, 0
	s_cbranch_scc1 .Lconv_nobal
	s_cmp_lg_u32 s34, 0x100
	s_cbranch_scc1 .Lconv_nobal
	s_and_b32 s80, s2, 7
	s_cmp_eq_u32 s80, 0
	s_cbranch_scc1 .LBB0_705
	s_lshr_b32 s80, s2, 3
	s_sub_i32 s70, s2, s80
	s_add_i32 s70, s70, -1
	s_movk_i32 s97, 0xe0
.Lconv_nobal:
	s_cmp_ge_i32 s70, s71
	s_cbranch_scc1 .LBB0_705
	s_mul_i32 s80, s72, 0xf800
	s_add_u32 s84, s84, s80
	s_addc_u32 s85, s85, 0
	global_load_dword v92, v143, s[84:85]
	s_add_u32 s84, s84, 0x800
	s_addc_u32 s85, s85, 0
	global_load_dword v93, v143, s[84:85]
	s_add_u32 s84, s84, 0x800
	s_addc_u32 s85, s85, 0
	global_load_dword v94, v143, s[84:85]
	s_add_u32 s84, s84, 0x800
	s_addc_u32 s85, s85, 0
	global_load_dword v95, v143, s[84:85]
	s_add_u32 s84, s84, 0x800
	s_addc_u32 s85, s85, 0
	global_load_dword v96, v143, s[84:85]
	s_add_u32 s84, s84, 0x800
	s_addc_u32 s85, s85, 0
	global_load_dword v97, v143, s[84:85]
	s_add_u32 s84, s84, 0x800
	s_addc_u32 s85, s85, 0
	global_load_dword v98, v143, s[84:85]
	s_add_u32 s84, s84, 0x800
	s_addc_u32 s85, s85, 0
	global_load_dword v99, v143, s[84:85]
	s_add_u32 s84, s84, 0x800
	s_addc_u32 s85, s85, 0
	global_load_dword v100, v143, s[84:85]
	s_add_u32 s84, s84, 0x800
	s_addc_u32 s85, s85, 0
	global_load_dword v101, v143, s[84:85]
	s_add_u32 s84, s84, 0x800
	s_addc_u32 s85, s85, 0
	global_load_dword v102, v143, s[84:85]
	s_add_u32 s84, s84, 0x800
	s_addc_u32 s85, s85, 0
	global_load_dword v103, v143, s[84:85]
	s_add_u32 s84, s84, 0x800
	s_addc_u32 s85, s85, 0
	global_load_dword v104, v143, s[84:85]
	s_add_u32 s84, s84, 0x800
	s_addc_u32 s85, s85, 0
	global_load_dword v105, v143, s[84:85]
	s_add_u32 s84, s84, 0x800
	s_addc_u32 s85, s85, 0
	global_load_dword v106, v143, s[84:85]
	s_add_u32 s84, s84, 0x800
	s_addc_u32 s85, s85, 0
	global_load_dword v107, v143, s[84:85]
	s_add_u32 s84, s84, 0x800
	s_addc_u32 s85, s85, 0
	global_load_dword v108, v143, s[84:85]
	s_add_u32 s84, s84, 0x800
	s_addc_u32 s85, s85, 0
	global_load_dword v109, v143, s[84:85]
	s_add_u32 s84, s84, 0x800
	s_addc_u32 s85, s85, 0
	global_load_dword v110, v143, s[84:85]
	s_add_u32 s84, s84, 0x800
	s_addc_u32 s85, s85, 0
	global_load_dword v111, v143, s[84:85]
	s_add_u32 s84, s84, 0x800
	s_addc_u32 s85, s85, 0
	global_load_dword v112, v143, s[84:85]
	s_add_u32 s84, s84, 0x800
	s_addc_u32 s85, s85, 0
	global_load_dword v113, v143, s[84:85]
	s_add_u32 s84, s84, 0x800
	s_addc_u32 s85, s85, 0
	global_load_dword v114, v143, s[84:85]
	s_add_u32 s84, s84, 0x800
	s_addc_u32 s85, s85, 0
	global_load_dword v115, v143, s[84:85]
	s_add_u32 s84, s84, 0x800
	s_addc_u32 s85, s85, 0
	global_load_dword v116, v143, s[84:85]
	s_add_u32 s84, s84, 0x800
	s_addc_u32 s85, s85, 0
	global_load_dword v117, v143, s[84:85]
	s_add_u32 s84, s84, 0x800
	s_addc_u32 s85, s85, 0
	global_load_dword v118, v143, s[84:85]
	s_add_u32 s84, s84, 0x800
	s_addc_u32 s85, s85, 0
	global_load_dword v119, v143, s[84:85]
	s_add_u32 s84, s84, 0x800
	s_addc_u32 s85, s85, 0
	global_load_dword v120, v143, s[84:85]
	s_add_u32 s84, s84, 0x800
	s_addc_u32 s85, s85, 0
	global_load_dword v121, v143, s[84:85]
	s_add_u32 s84, s84, 0x800
	s_addc_u32 s85, s85, 0
	global_load_dword v122, v143, s[84:85]
	s_lshl_b32 s80, s72, 11
	s_add_u32 s86, s86, s80
	s_addc_u32 s87, s87, 0
	s_add_u32 s90, s90, s80
	s_addc_u32 s91, s91, 0
	s_add_u32 s92, s92, s80
	s_addc_u32 s93, s93, 0
	global_load_dword v123, v143, s[86:87]
	global_load_dword v124, v143, s[90:91]
	global_load_dword v125, v143, s[92:93]
	s_waitcnt vmcnt(0)
	s_lshl_b32 s73, s70, 4
	s_and_b32 s74, s73, 0xfffff000
	s_add_i32 s75, s74, 0xfff
	s_and_b32 s80, s73, 0x7fffff00
	s_add_i32 s81, s80, 0xff
	s_cmpk_lt_i32 s70, 0x400
	s_cselect_b32 s74, s74, s80
	s_cselect_b32 s75, s75, s81
	s_add_i32 s80, s73, -15
	s_max_i32 s80, s80, s74
	s_mul_i32 s80, s80, 0x1800
	s_add_u32 s82, s42, s80
	s_addc_u32 s83, s43, 0
	global_load_ushort v0, v142, s[82:83] offset:3712
	s_add_i32 s80, s73, -14
	s_max_i32 s80, s80, s74
	s_mul_i32 s80, s80, 0x1800
	s_add_u32 s82, s42, s80
	s_addc_u32 s83, s43, 0
	global_load_ushort v1, v142, s[82:83] offset:3712
	s_add_i32 s80, s73, -13
	s_max_i32 s80, s80, s74
	s_mul_i32 s80, s80, 0x1800
	s_add_u32 s82, s42, s80
	s_addc_u32 s83, s43, 0
	global_load_ushort v2, v142, s[82:83] offset:3712
	s_add_i32 s80, s73, -12
	s_max_i32 s80, s80, s74
	s_mul_i32 s80, s80, 0x1800
	s_add_u32 s82, s42, s80
	s_addc_u32 s83, s43, 0
	global_load_ushort v3, v142, s[82:83] offset:3712
	s_add_i32 s80, s73, -11
	s_max_i32 s80, s80, s74
	s_mul_i32 s80, s80, 0x1800
	s_add_u32 s82, s42, s80
	s_addc_u32 s83, s43, 0
	global_load_ushort v4, v142, s[82:83] offset:3712
	s_add_i32 s80, s73, -10
	s_max_i32 s80, s80, s74
	s_mul_i32 s80, s80, 0x1800
	s_add_u32 s82, s42, s80
	s_addc_u32 s83, s43, 0
	global_load_ushort v5, v142, s[82:83] offset:3712
	s_add_i32 s80, s73, -9
	s_max_i32 s80, s80, s74
	s_mul_i32 s80, s80, 0x1800
	s_add_u32 s82, s42, s80
	s_addc_u32 s83, s43, 0
	global_load_ushort v6, v142, s[82:83] offset:3712
	s_add_i32 s80, s73, -8
	s_max_i32 s80, s80, s74
	s_mul_i32 s80, s80, 0x1800
	s_add_u32 s82, s42, s80
	s_addc_u32 s83, s43, 0
	global_load_ushort v7, v142, s[82:83] offset:3712
	s_add_i32 s80, s73, -7
	s_max_i32 s80, s80, s74
	s_mul_i32 s80, s80, 0x1800
	s_add_u32 s82, s42, s80
	s_addc_u32 s83, s43, 0
	global_load_ushort v8, v142, s[82:83] offset:3712
	s_add_i32 s80, s73, -6
	s_max_i32 s80, s80, s74
	s_mul_i32 s80, s80, 0x1800
	s_add_u32 s82, s42, s80
	s_addc_u32 s83, s43, 0
	global_load_ushort v9, v142, s[82:83] offset:3712
	s_add_i32 s80, s73, -5
	s_max_i32 s80, s80, s74
	s_mul_i32 s80, s80, 0x1800
	s_add_u32 s82, s42, s80
	s_addc_u32 s83, s43, 0
	global_load_ushort v10, v142, s[82:83] offset:3712
	s_add_i32 s80, s73, -4
	s_max_i32 s80, s80, s74
	s_mul_i32 s80, s80, 0x1800
	s_add_u32 s82, s42, s80
	s_addc_u32 s83, s43, 0
	global_load_ushort v11, v142, s[82:83] offset:3712
	s_add_i32 s80, s73, -3
	s_max_i32 s80, s80, s74
	s_mul_i32 s80, s80, 0x1800
	s_add_u32 s82, s42, s80
	s_addc_u32 s83, s43, 0
	global_load_ushort v12, v142, s[82:83] offset:3712
	s_add_i32 s80, s73, -2
	s_max_i32 s80, s80, s74
	s_mul_i32 s80, s80, 0x1800
	s_add_u32 s82, s42, s80
	s_addc_u32 s83, s43, 0
	global_load_ushort v13, v142, s[82:83] offset:3712
	s_add_i32 s80, s73, -1
	s_max_i32 s80, s80, s74
	s_mul_i32 s80, s80, 0x1800
	s_add_u32 s82, s42, s80
	s_addc_u32 s83, s43, 0
	global_load_ushort v14, v142, s[82:83] offset:3712
	s_add_i32 s80, s73, 0
	s_mul_i32 s80, s80, 0x1800
	s_add_u32 s82, s42, s80
	s_addc_u32 s83, s43, 0
	global_load_ushort v15, v142, s[82:83] offset:3712
	s_add_i32 s80, s73, 1
	s_mul_i32 s80, s80, 0x1800
	s_add_u32 s82, s42, s80
	s_addc_u32 s83, s43, 0
	global_load_ushort v16, v142, s[82:83] offset:3712
	s_add_i32 s80, s73, 2
	s_mul_i32 s80, s80, 0x1800
	s_add_u32 s82, s42, s80
	s_addc_u32 s83, s43, 0
	global_load_ushort v17, v142, s[82:83] offset:3712
	s_add_i32 s80, s73, 3
	s_mul_i32 s80, s80, 0x1800
	s_add_u32 s82, s42, s80
	s_addc_u32 s83, s43, 0
	global_load_ushort v18, v142, s[82:83] offset:3712
	s_add_i32 s80, s73, 4
	s_mul_i32 s80, s80, 0x1800
	s_add_u32 s82, s42, s80
	s_addc_u32 s83, s43, 0
	global_load_ushort v19, v142, s[82:83] offset:3712
	s_add_i32 s80, s73, 5
	s_mul_i32 s80, s80, 0x1800
	s_add_u32 s82, s42, s80
	s_addc_u32 s83, s43, 0
	global_load_ushort v20, v142, s[82:83] offset:3712
	s_add_i32 s80, s73, 6
	s_mul_i32 s80, s80, 0x1800
	s_add_u32 s82, s42, s80
	s_addc_u32 s83, s43, 0
	global_load_ushort v21, v142, s[82:83] offset:3712
	s_add_i32 s80, s73, 7
	s_mul_i32 s80, s80, 0x1800
	s_add_u32 s82, s42, s80
	s_addc_u32 s83, s43, 0
	global_load_ushort v22, v142, s[82:83] offset:3712
	s_add_i32 s80, s73, 8
	s_mul_i32 s80, s80, 0x1800
	s_add_u32 s82, s42, s80
	s_addc_u32 s83, s43, 0
	global_load_ushort v23, v142, s[82:83] offset:3712
	s_add_i32 s80, s73, 9
	s_mul_i32 s80, s80, 0x1800
	s_add_u32 s82, s42, s80
	s_addc_u32 s83, s43, 0
	global_load_ushort v24, v142, s[82:83] offset:3712
	s_add_i32 s80, s73, 10
	s_mul_i32 s80, s80, 0x1800
	s_add_u32 s82, s42, s80
	s_addc_u32 s83, s43, 0
	global_load_ushort v25, v142, s[82:83] offset:3712
	s_add_i32 s80, s73, 11
	s_mul_i32 s80, s80, 0x1800
	s_add_u32 s82, s42, s80
	s_addc_u32 s83, s43, 0
	global_load_ushort v26, v142, s[82:83] offset:3712
	s_add_i32 s80, s73, 12
	s_mul_i32 s80, s80, 0x1800
	s_add_u32 s82, s42, s80
	s_addc_u32 s83, s43, 0
	global_load_ushort v27, v142, s[82:83] offset:3712
	s_add_i32 s80, s73, 13
	s_mul_i32 s80, s80, 0x1800
	s_add_u32 s82, s42, s80
	s_addc_u32 s83, s43, 0
	global_load_ushort v28, v142, s[82:83] offset:3712
	s_add_i32 s80, s73, 14
	s_mul_i32 s80, s80, 0x1800
	s_add_u32 s82, s42, s80
	s_addc_u32 s83, s43, 0
	global_load_ushort v29, v142, s[82:83] offset:3712
	s_add_i32 s80, s73, 15
	s_mul_i32 s80, s80, 0x1800
	s_add_u32 s82, s42, s80
	s_addc_u32 s83, s43, 0
	global_load_ushort v30, v142, s[82:83] offset:3712
	s_add_i32 s80, s73, 16
	s_min_i32 s80, s80, s75
	s_mul_i32 s80, s80, 0x1800
	s_add_u32 s82, s42, s80
	s_addc_u32 s83, s43, 0
	global_load_ushort v31, v142, s[82:83] offset:3712
	s_add_i32 s80, s73, 17
	s_min_i32 s80, s80, s75
	s_mul_i32 s80, s80, 0x1800
	s_add_u32 s82, s42, s80
	s_addc_u32 s83, s43, 0
	global_load_ushort v32, v142, s[82:83] offset:3712
	s_add_i32 s80, s73, 18
	s_min_i32 s80, s80, s75
	s_mul_i32 s80, s80, 0x1800
	s_add_u32 s82, s42, s80
	s_addc_u32 s83, s43, 0
	global_load_ushort v33, v142, s[82:83] offset:3712
	s_add_i32 s80, s73, 19
	s_min_i32 s80, s80, s75
	s_mul_i32 s80, s80, 0x1800
	s_add_u32 s82, s42, s80
	s_addc_u32 s83, s43, 0
	global_load_ushort v34, v142, s[82:83] offset:3712
	s_add_i32 s80, s73, 20
	s_min_i32 s80, s80, s75
	s_mul_i32 s80, s80, 0x1800
	s_add_u32 s82, s42, s80
	s_addc_u32 s83, s43, 0
	global_load_ushort v35, v142, s[82:83] offset:3712
	s_add_i32 s80, s73, 21
	s_min_i32 s80, s80, s75
	s_mul_i32 s80, s80, 0x1800
	s_add_u32 s82, s42, s80
	s_addc_u32 s83, s43, 0
	global_load_ushort v36, v142, s[82:83] offset:3712
	s_add_i32 s80, s73, 22
	s_min_i32 s80, s80, s75
	s_mul_i32 s80, s80, 0x1800
	s_add_u32 s82, s42, s80
	s_addc_u32 s83, s43, 0
	global_load_ushort v37, v142, s[82:83] offset:3712
	s_add_i32 s80, s73, 23
	s_min_i32 s80, s80, s75
	s_mul_i32 s80, s80, 0x1800
	s_add_u32 s82, s42, s80
	s_addc_u32 s83, s43, 0
	global_load_ushort v38, v142, s[82:83] offset:3712
	s_add_i32 s80, s73, 24
	s_min_i32 s80, s80, s75
	s_mul_i32 s80, s80, 0x1800
	s_add_u32 s82, s42, s80
	s_addc_u32 s83, s43, 0
	global_load_ushort v39, v142, s[82:83] offset:3712
	s_add_i32 s80, s73, 25
	s_min_i32 s80, s80, s75
	s_mul_i32 s80, s80, 0x1800
	s_add_u32 s82, s42, s80
	s_addc_u32 s83, s43, 0
	global_load_ushort v40, v142, s[82:83] offset:3712
	s_add_i32 s80, s73, 26
	s_min_i32 s80, s80, s75
	s_mul_i32 s80, s80, 0x1800
	s_add_u32 s82, s42, s80
	s_addc_u32 s83, s43, 0
	global_load_ushort v41, v142, s[82:83] offset:3712
	s_add_i32 s80, s73, 27
	s_min_i32 s80, s80, s75
	s_mul_i32 s80, s80, 0x1800
	s_add_u32 s82, s42, s80
	s_addc_u32 s83, s43, 0
	global_load_ushort v42, v142, s[82:83] offset:3712
	s_add_i32 s80, s73, 28
	s_min_i32 s80, s80, s75
	s_mul_i32 s80, s80, 0x1800
	s_add_u32 s82, s42, s80
	s_addc_u32 s83, s43, 0
	global_load_ushort v43, v142, s[82:83] offset:3712
	s_add_i32 s80, s73, 29
	s_min_i32 s80, s80, s75
	s_mul_i32 s80, s80, 0x1800
	s_add_u32 s82, s42, s80
	s_addc_u32 s83, s43, 0
	global_load_ushort v44, v142, s[82:83] offset:3712
	s_add_i32 s80, s73, 30
	s_min_i32 s80, s80, s75
	s_mul_i32 s80, s80, 0x1800
	s_add_u32 s82, s42, s80
	s_addc_u32 s83, s43, 0
	global_load_ushort v45, v142, s[82:83] offset:3712
	s_waitcnt vmcnt(0)
.Lconv_loop:
	s_waitcnt vmcnt(16)
	s_lshl_b32 s73, s70, 4
	s_and_b32 s74, s73, 0xfffff000
	s_add_i32 s75, s74, 0xfff
	s_and_b32 s80, s73, 0x7fffff00
	s_add_i32 s81, s80, 0xff
	s_cmpk_lt_i32 s70, 0x400
	s_cselect_b32 s74, s74, s80
	s_cselect_b32 s75, s75, s81
	s_cmp_eq_u32 s73, s74
	s_cselect_b64 s[76:77], -1, 0
	s_add_i32 s80, s73, 15
	s_cmp_eq_u32 s80, s75
	s_cselect_b64 s[94:95], -1, 0
	v_lshlrev_b32_e32 v46, 16, v0
	v_lshlrev_b32_e32 v47, 16, v1
	v_lshlrev_b32_e32 v48, 16, v2
	v_lshlrev_b32_e32 v49, 16, v3
	v_lshlrev_b32_e32 v50, 16, v4
	v_lshlrev_b32_e32 v51, 16, v5
	v_lshlrev_b32_e32 v52, 16, v6
	v_lshlrev_b32_e32 v53, 16, v7
	v_lshlrev_b32_e32 v54, 16, v8
	v_lshlrev_b32_e32 v55, 16, v9
	v_lshlrev_b32_e32 v56, 16, v10
	v_lshlrev_b32_e32 v57, 16, v11
	v_lshlrev_b32_e32 v58, 16, v12
	v_lshlrev_b32_e32 v59, 16, v13
	v_lshlrev_b32_e32 v60, 16, v14
	v_lshlrev_b32_e32 v61, 16, v15
	v_lshlrev_b32_e32 v62, 16, v16
	v_lshlrev_b32_e32 v63, 16, v17
	v_lshlrev_b32_e32 v64, 16, v18
	v_lshlrev_b32_e32 v65, 16, v19
	v_lshlrev_b32_e32 v66, 16, v20
	v_lshlrev_b32_e32 v67, 16, v21
	v_lshlrev_b32_e32 v68, 16, v22
	v_lshlrev_b32_e32 v69, 16, v23
	v_lshlrev_b32_e32 v70, 16, v24
	v_lshlrev_b32_e32 v71, 16, v25
	v_lshlrev_b32_e32 v72, 16, v26
	v_lshlrev_b32_e32 v73, 16, v27
	v_lshlrev_b32_e32 v74, 16, v28
	v_lshlrev_b32_e32 v75, 16, v29
	v_lshlrev_b32_e32 v76, 16, v30
	v_lshlrev_b32_e32 v77, 16, v31
	v_lshlrev_b32_e32 v78, 16, v32
	v_lshlrev_b32_e32 v79, 16, v33
	v_lshlrev_b32_e32 v80, 16, v34
	v_lshlrev_b32_e32 v81, 16, v35
	v_lshlrev_b32_e32 v82, 16, v36
	v_lshlrev_b32_e32 v83, 16, v37
	v_lshlrev_b32_e32 v84, 16, v38
	v_lshlrev_b32_e32 v85, 16, v39
	v_lshlrev_b32_e32 v86, 16, v40
	v_lshlrev_b32_e32 v87, 16, v41
	v_lshlrev_b32_e32 v88, 16, v42
	v_lshlrev_b32_e32 v89, 16, v43
	v_lshlrev_b32_e32 v90, 16, v44
	v_lshlrev_b32_e32 v91, 16, v45
	v_cndmask_b32_e64 v46, v46, 0, s[76:77]
	v_cndmask_b32_e64 v47, v47, 0, s[76:77]
	v_cndmask_b32_e64 v48, v48, 0, s[76:77]
	v_cndmask_b32_e64 v49, v49, 0, s[76:77]
	v_cndmask_b32_e64 v50, v50, 0, s[76:77]
	v_cndmask_b32_e64 v51, v51, 0, s[76:77]
	v_cndmask_b32_e64 v52, v52, 0, s[76:77]
	v_cndmask_b32_e64 v53, v53, 0, s[76:77]
	v_cndmask_b32_e64 v54, v54, 0, s[76:77]
	v_cndmask_b32_e64 v55, v55, 0, s[76:77]
	v_cndmask_b32_e64 v56, v56, 0, s[76:77]
	v_cndmask_b32_e64 v57, v57, 0, s[76:77]
	v_cndmask_b32_e64 v58, v58, 0, s[76:77]
	v_cndmask_b32_e64 v59, v59, 0, s[76:77]
	v_cndmask_b32_e64 v60, v60, 0, s[76:77]
	v_cndmask_b32_e64 v77, v77, 0, s[94:95]
	v_cndmask_b32_e64 v78, v78, 0, s[94:95]
	v_cndmask_b32_e64 v79, v79, 0, s[94:95]
	v_cndmask_b32_e64 v80, v80, 0, s[94:95]
	v_cndmask_b32_e64 v81, v81, 0, s[94:95]
	v_cndmask_b32_e64 v82, v82, 0, s[94:95]
	v_cndmask_b32_e64 v83, v83, 0, s[94:95]
	v_cndmask_b32_e64 v84, v84, 0, s[94:95]
	v_cndmask_b32_e64 v85, v85, 0, s[94:95]
	v_cndmask_b32_e64 v86, v86, 0, s[94:95]
	v_cndmask_b32_e64 v87, v87, 0, s[94:95]
	v_cndmask_b32_e64 v88, v88, 0, s[94:95]
	v_cndmask_b32_e64 v89, v89, 0, s[94:95]
	v_cndmask_b32_e64 v90, v90, 0, s[94:95]
	v_cndmask_b32_e64 v91, v91, 0, s[94:95]
	s_add_i32 s96, s70, s97
	s_cmp_ge_i32 s96, s71
	s_cselect_b32 s96, s70, s96
	s_lshl_b32 s73, s96, 4
	s_and_b32 s74, s73, 0xfffff000
	s_add_i32 s75, s74, 0xfff
	s_and_b32 s80, s73, 0x7fffff00
	s_add_i32 s81, s80, 0xff
	s_cmpk_lt_i32 s96, 0x400
	s_cselect_b32 s74, s74, s80
	s_cselect_b32 s75, s75, s81
	s_add_i32 s80, s73, -15
	s_max_i32 s80, s80, s74
	s_mul_i32 s80, s80, 0x1800
	s_add_u32 s82, s42, s80
	s_addc_u32 s83, s43, 0
	global_load_ushort v0, v142, s[82:83] offset:3712
	s_add_i32 s80, s73, -14
	s_max_i32 s80, s80, s74
	s_mul_i32 s80, s80, 0x1800
	s_add_u32 s82, s42, s80
	s_addc_u32 s83, s43, 0
	global_load_ushort v1, v142, s[82:83] offset:3712
	s_add_i32 s80, s73, -13
	s_max_i32 s80, s80, s74
	s_mul_i32 s80, s80, 0x1800
	s_add_u32 s82, s42, s80
	s_addc_u32 s83, s43, 0
	global_load_ushort v2, v142, s[82:83] offset:3712
	s_add_i32 s80, s73, -12
	s_max_i32 s80, s80, s74
	s_mul_i32 s80, s80, 0x1800
	s_add_u32 s82, s42, s80
	s_addc_u32 s83, s43, 0
	global_load_ushort v3, v142, s[82:83] offset:3712
	s_add_i32 s80, s73, -11
	s_max_i32 s80, s80, s74
	s_mul_i32 s80, s80, 0x1800
	s_add_u32 s82, s42, s80
	s_addc_u32 s83, s43, 0
	global_load_ushort v4, v142, s[82:83] offset:3712
	s_add_i32 s80, s73, -10
	s_max_i32 s80, s80, s74
	s_mul_i32 s80, s80, 0x1800
	s_add_u32 s82, s42, s80
	s_addc_u32 s83, s43, 0
	global_load_ushort v5, v142, s[82:83] offset:3712
	s_add_i32 s80, s73, -9
	s_max_i32 s80, s80, s74
	s_mul_i32 s80, s80, 0x1800
	s_add_u32 s82, s42, s80
	s_addc_u32 s83, s43, 0
	global_load_ushort v6, v142, s[82:83] offset:3712
	s_add_i32 s80, s73, -8
	s_max_i32 s80, s80, s74
	s_mul_i32 s80, s80, 0x1800
	s_add_u32 s82, s42, s80
	s_addc_u32 s83, s43, 0
	global_load_ushort v7, v142, s[82:83] offset:3712
	s_add_i32 s80, s73, -7
	s_max_i32 s80, s80, s74
	s_mul_i32 s80, s80, 0x1800
	s_add_u32 s82, s42, s80
	s_addc_u32 s83, s43, 0
	global_load_ushort v8, v142, s[82:83] offset:3712
	s_add_i32 s80, s73, -6
	s_max_i32 s80, s80, s74
	s_mul_i32 s80, s80, 0x1800
	s_add_u32 s82, s42, s80
	s_addc_u32 s83, s43, 0
	global_load_ushort v9, v142, s[82:83] offset:3712
	s_add_i32 s80, s73, -5
	s_max_i32 s80, s80, s74
	s_mul_i32 s80, s80, 0x1800
	s_add_u32 s82, s42, s80
	s_addc_u32 s83, s43, 0
	global_load_ushort v10, v142, s[82:83] offset:3712
	s_add_i32 s80, s73, -4
	s_max_i32 s80, s80, s74
	s_mul_i32 s80, s80, 0x1800
	s_add_u32 s82, s42, s80
	s_addc_u32 s83, s43, 0
	global_load_ushort v11, v142, s[82:83] offset:3712
	s_add_i32 s80, s73, -3
	s_max_i32 s80, s80, s74
	s_mul_i32 s80, s80, 0x1800
	s_add_u32 s82, s42, s80
	s_addc_u32 s83, s43, 0
	global_load_ushort v12, v142, s[82:83] offset:3712
	s_add_i32 s80, s73, -2
	s_max_i32 s80, s80, s74
	s_mul_i32 s80, s80, 0x1800
	s_add_u32 s82, s42, s80
	s_addc_u32 s83, s43, 0
	global_load_ushort v13, v142, s[82:83] offset:3712
	s_add_i32 s80, s73, -1
	s_max_i32 s80, s80, s74
	s_mul_i32 s80, s80, 0x1800
	s_add_u32 s82, s42, s80
	s_addc_u32 s83, s43, 0
	global_load_ushort v14, v142, s[82:83] offset:3712
	s_add_i32 s80, s73, 0
	s_mul_i32 s80, s80, 0x1800
	s_add_u32 s82, s42, s80
	s_addc_u32 s83, s43, 0
	global_load_ushort v15, v142, s[82:83] offset:3712
	s_add_i32 s80, s73, 1
	s_mul_i32 s80, s80, 0x1800
	s_add_u32 s82, s42, s80
	s_addc_u32 s83, s43, 0
	global_load_ushort v16, v142, s[82:83] offset:3712
	s_add_i32 s80, s73, 2
	s_mul_i32 s80, s80, 0x1800
	s_add_u32 s82, s42, s80
	s_addc_u32 s83, s43, 0
	global_load_ushort v17, v142, s[82:83] offset:3712
	s_add_i32 s80, s73, 3
	s_mul_i32 s80, s80, 0x1800
	s_add_u32 s82, s42, s80
	s_addc_u32 s83, s43, 0
	global_load_ushort v18, v142, s[82:83] offset:3712
	s_add_i32 s80, s73, 4
	s_mul_i32 s80, s80, 0x1800
	s_add_u32 s82, s42, s80
	s_addc_u32 s83, s43, 0
	global_load_ushort v19, v142, s[82:83] offset:3712
	s_add_i32 s80, s73, 5
	s_mul_i32 s80, s80, 0x1800
	s_add_u32 s82, s42, s80
	s_addc_u32 s83, s43, 0
	global_load_ushort v20, v142, s[82:83] offset:3712
	s_add_i32 s80, s73, 6
	s_mul_i32 s80, s80, 0x1800
	s_add_u32 s82, s42, s80
	s_addc_u32 s83, s43, 0
	global_load_ushort v21, v142, s[82:83] offset:3712
	s_add_i32 s80, s73, 7
	s_mul_i32 s80, s80, 0x1800
	s_add_u32 s82, s42, s80
	s_addc_u32 s83, s43, 0
	global_load_ushort v22, v142, s[82:83] offset:3712
	s_add_i32 s80, s73, 8
	s_mul_i32 s80, s80, 0x1800
	s_add_u32 s82, s42, s80
	s_addc_u32 s83, s43, 0
	global_load_ushort v23, v142, s[82:83] offset:3712
	s_add_i32 s80, s73, 9
	s_mul_i32 s80, s80, 0x1800
	s_add_u32 s82, s42, s80
	s_addc_u32 s83, s43, 0
	global_load_ushort v24, v142, s[82:83] offset:3712
	s_add_i32 s80, s73, 10
	s_mul_i32 s80, s80, 0x1800
	s_add_u32 s82, s42, s80
	s_addc_u32 s83, s43, 0
	global_load_ushort v25, v142, s[82:83] offset:3712
	s_add_i32 s80, s73, 11
	s_mul_i32 s80, s80, 0x1800
	s_add_u32 s82, s42, s80
	s_addc_u32 s83, s43, 0
	global_load_ushort v26, v142, s[82:83] offset:3712
	s_add_i32 s80, s73, 12
	s_mul_i32 s80, s80, 0x1800
	s_add_u32 s82, s42, s80
	s_addc_u32 s83, s43, 0
	global_load_ushort v27, v142, s[82:83] offset:3712
	s_add_i32 s80, s73, 13
	s_mul_i32 s80, s80, 0x1800
	s_add_u32 s82, s42, s80
	s_addc_u32 s83, s43, 0
	global_load_ushort v28, v142, s[82:83] offset:3712
	s_add_i32 s80, s73, 14
	s_mul_i32 s80, s80, 0x1800
	s_add_u32 s82, s42, s80
	s_addc_u32 s83, s43, 0
	global_load_ushort v29, v142, s[82:83] offset:3712
	s_add_i32 s80, s73, 15
	s_mul_i32 s80, s80, 0x1800
	s_add_u32 s82, s42, s80
	s_addc_u32 s83, s43, 0
	global_load_ushort v30, v142, s[82:83] offset:3712
	s_add_i32 s80, s73, 16
	s_min_i32 s80, s80, s75
	s_mul_i32 s80, s80, 0x1800
	s_add_u32 s82, s42, s80
	s_addc_u32 s83, s43, 0
	global_load_ushort v31, v142, s[82:83] offset:3712
	s_add_i32 s80, s73, 17
	s_min_i32 s80, s80, s75
	s_mul_i32 s80, s80, 0x1800
	s_add_u32 s82, s42, s80
	s_addc_u32 s83, s43, 0
	global_load_ushort v32, v142, s[82:83] offset:3712
	s_add_i32 s80, s73, 18
	s_min_i32 s80, s80, s75
	s_mul_i32 s80, s80, 0x1800
	s_add_u32 s82, s42, s80
	s_addc_u32 s83, s43, 0
	global_load_ushort v33, v142, s[82:83] offset:3712
	s_add_i32 s80, s73, 19
	s_min_i32 s80, s80, s75
	s_mul_i32 s80, s80, 0x1800
	s_add_u32 s82, s42, s80
	s_addc_u32 s83, s43, 0
	global_load_ushort v34, v142, s[82:83] offset:3712
	s_add_i32 s80, s73, 20
	s_min_i32 s80, s80, s75
	s_mul_i32 s80, s80, 0x1800
	s_add_u32 s82, s42, s80
	s_addc_u32 s83, s43, 0
	global_load_ushort v35, v142, s[82:83] offset:3712
	s_add_i32 s80, s73, 21
	s_min_i32 s80, s80, s75
	s_mul_i32 s80, s80, 0x1800
	s_add_u32 s82, s42, s80
	s_addc_u32 s83, s43, 0
	global_load_ushort v36, v142, s[82:83] offset:3712
	s_add_i32 s80, s73, 22
	s_min_i32 s80, s80, s75
	s_mul_i32 s80, s80, 0x1800
	s_add_u32 s82, s42, s80
	s_addc_u32 s83, s43, 0
	global_load_ushort v37, v142, s[82:83] offset:3712
	s_add_i32 s80, s73, 23
	s_min_i32 s80, s80, s75
	s_mul_i32 s80, s80, 0x1800
	s_add_u32 s82, s42, s80
	s_addc_u32 s83, s43, 0
	global_load_ushort v38, v142, s[82:83] offset:3712
	s_add_i32 s80, s73, 24
	s_min_i32 s80, s80, s75
	s_mul_i32 s80, s80, 0x1800
	s_add_u32 s82, s42, s80
	s_addc_u32 s83, s43, 0
	global_load_ushort v39, v142, s[82:83] offset:3712
	s_add_i32 s80, s73, 25
	s_min_i32 s80, s80, s75
	s_mul_i32 s80, s80, 0x1800
	s_add_u32 s82, s42, s80
	s_addc_u32 s83, s43, 0
	global_load_ushort v40, v142, s[82:83] offset:3712
	s_add_i32 s80, s73, 26
	s_min_i32 s80, s80, s75
	s_mul_i32 s80, s80, 0x1800
	s_add_u32 s82, s42, s80
	s_addc_u32 s83, s43, 0
	global_load_ushort v41, v142, s[82:83] offset:3712
	s_add_i32 s80, s73, 27
	s_min_i32 s80, s80, s75
	s_mul_i32 s80, s80, 0x1800
	s_add_u32 s82, s42, s80
	s_addc_u32 s83, s43, 0
	global_load_ushort v42, v142, s[82:83] offset:3712
	s_add_i32 s80, s73, 28
	s_min_i32 s80, s80, s75
	s_mul_i32 s80, s80, 0x1800
	s_add_u32 s82, s42, s80
	s_addc_u32 s83, s43, 0
	global_load_ushort v43, v142, s[82:83] offset:3712
	s_add_i32 s80, s73, 29
	s_min_i32 s80, s80, s75
	s_mul_i32 s80, s80, 0x1800
	s_add_u32 s82, s42, s80
	s_addc_u32 s83, s43, 0
	global_load_ushort v44, v142, s[82:83] offset:3712
	s_add_i32 s80, s73, 30
	s_min_i32 s80, s80, s75
	s_mul_i32 s80, s80, 0x1800
	s_add_u32 s82, s42, s80
	s_addc_u32 s83, s43, 0
	global_load_ushort v45, v142, s[82:83] offset:3712
	v_mov_b32_e32 v126, v123
	v_mov_b32_e32 v127, v123
	v_mov_b32_e32 v128, v123
	v_mov_b32_e32 v129, v123
	v_mov_b32_e32 v130, v123
	v_mov_b32_e32 v131, v123
	v_mov_b32_e32 v132, v123
	v_mov_b32_e32 v133, v123
	v_mov_b32_e32 v134, v123
	v_mov_b32_e32 v135, v123
	v_mov_b32_e32 v136, v123
	v_mov_b32_e32 v137, v123
	v_mov_b32_e32 v138, v123
	v_mov_b32_e32 v139, v123
	v_mov_b32_e32 v140, v123
	v_mov_b32_e32 v141, v123
	v_fmac_f32_e32 v126, v92, v46
	v_fmac_f32_e32 v126, v93, v47
	v_fmac_f32_e32 v127, v92, v47
	v_fmac_f32_e32 v126, v94, v48
	v_fmac_f32_e32 v127, v93, v48
	v_fmac_f32_e32 v128, v92, v48
	v_fmac_f32_e32 v126, v95, v49
	v_fmac_f32_e32 v127, v94, v49
	v_fmac_f32_e32 v128, v93, v49
	v_fmac_f32_e32 v129, v92, v49
	v_fmac_f32_e32 v126, v96, v50
	v_fmac_f32_e32 v127, v95, v50
	v_fmac_f32_e32 v128, v94, v50
	v_fmac_f32_e32 v129, v93, v50
	v_fmac_f32_e32 v130, v92, v50
	v_fmac_f32_e32 v126, v97, v51
	v_fmac_f32_e32 v127, v96, v51
	v_fmac_f32_e32 v128, v95, v51
	v_fmac_f32_e32 v129, v94, v51
	v_fmac_f32_e32 v130, v93, v51
	v_fmac_f32_e32 v131, v92, v51
	v_fmac_f32_e32 v126, v98, v52
	v_fmac_f32_e32 v127, v97, v52
	v_fmac_f32_e32 v128, v96, v52
	v_fmac_f32_e32 v129, v95, v52
	v_fmac_f32_e32 v130, v94, v52
	v_fmac_f32_e32 v131, v93, v52
	v_fmac_f32_e32 v132, v92, v52
	v_fmac_f32_e32 v126, v99, v53
	v_fmac_f32_e32 v127, v98, v53
	v_fmac_f32_e32 v128, v97, v53
	v_fmac_f32_e32 v129, v96, v53
	v_fmac_f32_e32 v130, v95, v53
	v_fmac_f32_e32 v131, v94, v53
	v_fmac_f32_e32 v132, v93, v53
	v_fmac_f32_e32 v133, v92, v53
	v_fmac_f32_e32 v126, v100, v54
	v_fmac_f32_e32 v127, v99, v54
	v_fmac_f32_e32 v128, v98, v54
	v_fmac_f32_e32 v129, v97, v54
	v_fmac_f32_e32 v130, v96, v54
	v_fmac_f32_e32 v131, v95, v54
	v_fmac_f32_e32 v132, v94, v54
	v_fmac_f32_e32 v133, v93, v54
	v_fmac_f32_e32 v134, v92, v54
	v_fmac_f32_e32 v126, v101, v55
	v_fmac_f32_e32 v127, v100, v55
	v_fmac_f32_e32 v128, v99, v55
	v_fmac_f32_e32 v129, v98, v55
	v_fmac_f32_e32 v130, v97, v55
	v_fmac_f32_e32 v131, v96, v55
	v_fmac_f32_e32 v132, v95, v55
	v_fmac_f32_e32 v133, v94, v55
	v_fmac_f32_e32 v134, v93, v55
	v_fmac_f32_e32 v135, v92, v55
	v_fmac_f32_e32 v126, v102, v56
	v_fmac_f32_e32 v127, v101, v56
	v_fmac_f32_e32 v128, v100, v56
	v_fmac_f32_e32 v129, v99, v56
	v_fmac_f32_e32 v130, v98, v56
	v_fmac_f32_e32 v131, v97, v56
	v_fmac_f32_e32 v132, v96, v56
	v_fmac_f32_e32 v133, v95, v56
	v_fmac_f32_e32 v134, v94, v56
	v_fmac_f32_e32 v135, v93, v56
	v_fmac_f32_e32 v136, v92, v56
	v_fmac_f32_e32 v126, v103, v57
	v_fmac_f32_e32 v127, v102, v57
	v_fmac_f32_e32 v128, v101, v57
	v_fmac_f32_e32 v129, v100, v57
	v_fmac_f32_e32 v130, v99, v57
	v_fmac_f32_e32 v131, v98, v57
	v_fmac_f32_e32 v132, v97, v57
	v_fmac_f32_e32 v133, v96, v57
	v_fmac_f32_e32 v134, v95, v57
	v_fmac_f32_e32 v135, v94, v57
	v_fmac_f32_e32 v136, v93, v57
	v_fmac_f32_e32 v137, v92, v57
	v_fmac_f32_e32 v126, v104, v58
	v_fmac_f32_e32 v127, v103, v58
	v_fmac_f32_e32 v128, v102, v58
	v_fmac_f32_e32 v129, v101, v58
	v_fmac_f32_e32 v130, v100, v58
	v_fmac_f32_e32 v131, v99, v58
	v_fmac_f32_e32 v132, v98, v58
	v_fmac_f32_e32 v133, v97, v58
	v_fmac_f32_e32 v134, v96, v58
	v_fmac_f32_e32 v135, v95, v58
	v_fmac_f32_e32 v136, v94, v58
	v_fmac_f32_e32 v137, v93, v58
	v_fmac_f32_e32 v138, v92, v58
	v_fmac_f32_e32 v126, v105, v59
	v_fmac_f32_e32 v127, v104, v59
	v_fmac_f32_e32 v128, v103, v59
	v_fmac_f32_e32 v129, v102, v59
	v_fmac_f32_e32 v130, v101, v59
	v_fmac_f32_e32 v131, v100, v59
	v_fmac_f32_e32 v132, v99, v59
	v_fmac_f32_e32 v133, v98, v59
	v_fmac_f32_e32 v134, v97, v59
	v_fmac_f32_e32 v135, v96, v59
	v_fmac_f32_e32 v136, v95, v59
	v_fmac_f32_e32 v137, v94, v59
	v_fmac_f32_e32 v138, v93, v59
	v_fmac_f32_e32 v139, v92, v59
	v_fmac_f32_e32 v126, v106, v60
	v_fmac_f32_e32 v127, v105, v60
	v_fmac_f32_e32 v128, v104, v60
	v_fmac_f32_e32 v129, v103, v60
	v_fmac_f32_e32 v130, v102, v60
	v_fmac_f32_e32 v131, v101, v60
	v_fmac_f32_e32 v132, v100, v60
	v_fmac_f32_e32 v133, v99, v60
	v_fmac_f32_e32 v134, v98, v60
	v_fmac_f32_e32 v135, v97, v60
	v_fmac_f32_e32 v136, v96, v60
	v_fmac_f32_e32 v137, v95, v60
	v_fmac_f32_e32 v138, v94, v60
	v_fmac_f32_e32 v139, v93, v60
	v_fmac_f32_e32 v140, v92, v60
	v_fmac_f32_e32 v126, v107, v61
	v_fmac_f32_e32 v127, v106, v61
	v_fmac_f32_e32 v128, v105, v61
	v_fmac_f32_e32 v129, v104, v61
	v_fmac_f32_e32 v130, v103, v61
	v_fmac_f32_e32 v131, v102, v61
	v_fmac_f32_e32 v132, v101, v61
	v_fmac_f32_e32 v133, v100, v61
	v_fmac_f32_e32 v134, v99, v61
	v_fmac_f32_e32 v135, v98, v61
	v_fmac_f32_e32 v136, v97, v61
	v_fmac_f32_e32 v137, v96, v61
	v_fmac_f32_e32 v138, v95, v61
	v_fmac_f32_e32 v139, v94, v61
	v_fmac_f32_e32 v140, v93, v61
	v_fmac_f32_e32 v141, v92, v61
	v_fmac_f32_e32 v126, v108, v62
	v_fmac_f32_e32 v127, v107, v62
	v_fmac_f32_e32 v128, v106, v62
	v_fmac_f32_e32 v129, v105, v62
	v_fmac_f32_e32 v130, v104, v62
	v_fmac_f32_e32 v131, v103, v62
	v_fmac_f32_e32 v132, v102, v62
	v_fmac_f32_e32 v133, v101, v62
	v_fmac_f32_e32 v134, v100, v62
	v_fmac_f32_e32 v135, v99, v62
	v_fmac_f32_e32 v136, v98, v62
	v_fmac_f32_e32 v137, v97, v62
	v_fmac_f32_e32 v138, v96, v62
	v_fmac_f32_e32 v139, v95, v62
	v_fmac_f32_e32 v140, v94, v62
	v_fmac_f32_e32 v141, v93, v62
	v_fmac_f32_e32 v126, v109, v63
	v_fmac_f32_e32 v127, v108, v63
	v_fmac_f32_e32 v128, v107, v63
	v_fmac_f32_e32 v129, v106, v63
	v_fmac_f32_e32 v130, v105, v63
	v_fmac_f32_e32 v131, v104, v63
	v_fmac_f32_e32 v132, v103, v63
	v_fmac_f32_e32 v133, v102, v63
	v_fmac_f32_e32 v134, v101, v63
	v_fmac_f32_e32 v135, v100, v63
	v_fmac_f32_e32 v136, v99, v63
	v_fmac_f32_e32 v137, v98, v63
	v_fmac_f32_e32 v138, v97, v63
	v_fmac_f32_e32 v139, v96, v63
	v_fmac_f32_e32 v140, v95, v63
	v_fmac_f32_e32 v141, v94, v63
	v_fmac_f32_e32 v126, v110, v64
	v_fmac_f32_e32 v127, v109, v64
	v_fmac_f32_e32 v128, v108, v64
	v_fmac_f32_e32 v129, v107, v64
	v_fmac_f32_e32 v130, v106, v64
	v_fmac_f32_e32 v131, v105, v64
	v_fmac_f32_e32 v132, v104, v64
	v_fmac_f32_e32 v133, v103, v64
	v_fmac_f32_e32 v134, v102, v64
	v_fmac_f32_e32 v135, v101, v64
	v_fmac_f32_e32 v136, v100, v64
	v_fmac_f32_e32 v137, v99, v64
	v_fmac_f32_e32 v138, v98, v64
	v_fmac_f32_e32 v139, v97, v64
	v_fmac_f32_e32 v140, v96, v64
	v_fmac_f32_e32 v141, v95, v64
	v_fmac_f32_e32 v126, v111, v65
	v_fmac_f32_e32 v127, v110, v65
	v_fmac_f32_e32 v128, v109, v65
	v_fmac_f32_e32 v129, v108, v65
	v_fmac_f32_e32 v130, v107, v65
	v_fmac_f32_e32 v131, v106, v65
	v_fmac_f32_e32 v132, v105, v65
	v_fmac_f32_e32 v133, v104, v65
	v_fmac_f32_e32 v134, v103, v65
	v_fmac_f32_e32 v135, v102, v65
	v_fmac_f32_e32 v136, v101, v65
	v_fmac_f32_e32 v137, v100, v65
	v_fmac_f32_e32 v138, v99, v65
	v_fmac_f32_e32 v139, v98, v65
	v_fmac_f32_e32 v140, v97, v65
	v_fmac_f32_e32 v141, v96, v65
	v_fmac_f32_e32 v126, v112, v66
	v_fmac_f32_e32 v127, v111, v66
	v_fmac_f32_e32 v128, v110, v66
	v_fmac_f32_e32 v129, v109, v66
	v_fmac_f32_e32 v130, v108, v66
	v_fmac_f32_e32 v131, v107, v66
	v_fmac_f32_e32 v132, v106, v66
	v_fmac_f32_e32 v133, v105, v66
	v_fmac_f32_e32 v134, v104, v66
	v_fmac_f32_e32 v135, v103, v66
	v_fmac_f32_e32 v136, v102, v66
	v_fmac_f32_e32 v137, v101, v66
	v_fmac_f32_e32 v138, v100, v66
	v_fmac_f32_e32 v139, v99, v66
	v_fmac_f32_e32 v140, v98, v66
	v_fmac_f32_e32 v141, v97, v66
	v_fmac_f32_e32 v126, v113, v67
	v_fmac_f32_e32 v127, v112, v67
	v_fmac_f32_e32 v128, v111, v67
	v_fmac_f32_e32 v129, v110, v67
	v_fmac_f32_e32 v130, v109, v67
	v_fmac_f32_e32 v131, v108, v67
	v_fmac_f32_e32 v132, v107, v67
	v_fmac_f32_e32 v133, v106, v67
	v_fmac_f32_e32 v134, v105, v67
	v_fmac_f32_e32 v135, v104, v67
	v_fmac_f32_e32 v136, v103, v67
	v_fmac_f32_e32 v137, v102, v67
	v_fmac_f32_e32 v138, v101, v67
	v_fmac_f32_e32 v139, v100, v67
	v_fmac_f32_e32 v140, v99, v67
	v_fmac_f32_e32 v141, v98, v67
	v_fmac_f32_e32 v126, v114, v68
	v_fmac_f32_e32 v127, v113, v68
	v_fmac_f32_e32 v128, v112, v68
	v_fmac_f32_e32 v129, v111, v68
	v_fmac_f32_e32 v130, v110, v68
	v_fmac_f32_e32 v131, v109, v68
	v_fmac_f32_e32 v132, v108, v68
	v_fmac_f32_e32 v133, v107, v68
	v_fmac_f32_e32 v134, v106, v68
	v_fmac_f32_e32 v135, v105, v68
	v_fmac_f32_e32 v136, v104, v68
	v_fmac_f32_e32 v137, v103, v68
	v_fmac_f32_e32 v138, v102, v68
	v_fmac_f32_e32 v139, v101, v68
	v_fmac_f32_e32 v140, v100, v68
	v_fmac_f32_e32 v141, v99, v68
	v_fmac_f32_e32 v126, v115, v69
	v_fmac_f32_e32 v127, v114, v69
	v_fmac_f32_e32 v128, v113, v69
	v_fmac_f32_e32 v129, v112, v69
	v_fmac_f32_e32 v130, v111, v69
	v_fmac_f32_e32 v131, v110, v69
	v_fmac_f32_e32 v132, v109, v69
	v_fmac_f32_e32 v133, v108, v69
	v_fmac_f32_e32 v134, v107, v69
	v_fmac_f32_e32 v135, v106, v69
	v_fmac_f32_e32 v136, v105, v69
	v_fmac_f32_e32 v137, v104, v69
	v_fmac_f32_e32 v138, v103, v69
	v_fmac_f32_e32 v139, v102, v69
	v_fmac_f32_e32 v140, v101, v69
	v_fmac_f32_e32 v141, v100, v69
	v_fmac_f32_e32 v126, v116, v70
	v_fmac_f32_e32 v127, v115, v70
	v_fmac_f32_e32 v128, v114, v70
	v_fmac_f32_e32 v129, v113, v70
	v_fmac_f32_e32 v130, v112, v70
	v_fmac_f32_e32 v131, v111, v70
	v_fmac_f32_e32 v132, v110, v70
	v_fmac_f32_e32 v133, v109, v70
	v_fmac_f32_e32 v134, v108, v70
	v_fmac_f32_e32 v135, v107, v70
	v_fmac_f32_e32 v136, v106, v70
	v_fmac_f32_e32 v137, v105, v70
	v_fmac_f32_e32 v138, v104, v70
	v_fmac_f32_e32 v139, v103, v70
	v_fmac_f32_e32 v140, v102, v70
	v_fmac_f32_e32 v141, v101, v70
	v_fmac_f32_e32 v126, v117, v71
	v_fmac_f32_e32 v127, v116, v71
	v_fmac_f32_e32 v128, v115, v71
	v_fmac_f32_e32 v129, v114, v71
	v_fmac_f32_e32 v130, v113, v71
	v_fmac_f32_e32 v131, v112, v71
	v_fmac_f32_e32 v132, v111, v71
	v_fmac_f32_e32 v133, v110, v71
	v_fmac_f32_e32 v134, v109, v71
	v_fmac_f32_e32 v135, v108, v71
	v_fmac_f32_e32 v136, v107, v71
	v_fmac_f32_e32 v137, v106, v71
	v_fmac_f32_e32 v138, v105, v71
	v_fmac_f32_e32 v139, v104, v71
	v_fmac_f32_e32 v140, v103, v71
	v_fmac_f32_e32 v141, v102, v71
	v_fmac_f32_e32 v126, v118, v72
	v_fmac_f32_e32 v127, v117, v72
	v_fmac_f32_e32 v128, v116, v72
	v_fmac_f32_e32 v129, v115, v72
	v_fmac_f32_e32 v130, v114, v72
	v_fmac_f32_e32 v131, v113, v72
	v_fmac_f32_e32 v132, v112, v72
	v_fmac_f32_e32 v133, v111, v72
	v_fmac_f32_e32 v134, v110, v72
	v_fmac_f32_e32 v135, v109, v72
	v_fmac_f32_e32 v136, v108, v72
	v_fmac_f32_e32 v137, v107, v72
	v_fmac_f32_e32 v138, v106, v72
	v_fmac_f32_e32 v139, v105, v72
	v_fmac_f32_e32 v140, v104, v72
	v_fmac_f32_e32 v141, v103, v72
	v_fmac_f32_e32 v126, v119, v73
	v_fmac_f32_e32 v127, v118, v73
	v_fmac_f32_e32 v128, v117, v73
	v_fmac_f32_e32 v129, v116, v73
	v_fmac_f32_e32 v130, v115, v73
	v_fmac_f32_e32 v131, v114, v73
	v_fmac_f32_e32 v132, v113, v73
	v_fmac_f32_e32 v133, v112, v73
	v_fmac_f32_e32 v134, v111, v73
	v_fmac_f32_e32 v135, v110, v73
	v_fmac_f32_e32 v136, v109, v73
	v_fmac_f32_e32 v137, v108, v73
	v_fmac_f32_e32 v138, v107, v73
	v_fmac_f32_e32 v139, v106, v73
	v_fmac_f32_e32 v140, v105, v73
	v_fmac_f32_e32 v141, v104, v73
	v_fmac_f32_e32 v126, v120, v74
	v_fmac_f32_e32 v127, v119, v74
	v_fmac_f32_e32 v128, v118, v74
	v_fmac_f32_e32 v129, v117, v74
	v_fmac_f32_e32 v130, v116, v74
	v_fmac_f32_e32 v131, v115, v74
	v_fmac_f32_e32 v132, v114, v74
	v_fmac_f32_e32 v133, v113, v74
	v_fmac_f32_e32 v134, v112, v74
	v_fmac_f32_e32 v135, v111, v74
	v_fmac_f32_e32 v136, v110, v74
	v_fmac_f32_e32 v137, v109, v74
	v_fmac_f32_e32 v138, v108, v74
	v_fmac_f32_e32 v139, v107, v74
	v_fmac_f32_e32 v140, v106, v74
	v_fmac_f32_e32 v141, v105, v74
	v_fmac_f32_e32 v126, v121, v75
	v_fmac_f32_e32 v127, v120, v75
	v_fmac_f32_e32 v128, v119, v75
	v_fmac_f32_e32 v129, v118, v75
	v_fmac_f32_e32 v130, v117, v75
	v_fmac_f32_e32 v131, v116, v75
	v_fmac_f32_e32 v132, v115, v75
	v_fmac_f32_e32 v133, v114, v75
	v_fmac_f32_e32 v134, v113, v75
	v_fmac_f32_e32 v135, v112, v75
	v_fmac_f32_e32 v136, v111, v75
	v_fmac_f32_e32 v137, v110, v75
	v_fmac_f32_e32 v138, v109, v75
	v_fmac_f32_e32 v139, v108, v75
	v_fmac_f32_e32 v140, v107, v75
	v_fmac_f32_e32 v141, v106, v75
	v_fmac_f32_e32 v126, v122, v76
	v_fmac_f32_e32 v127, v121, v76
	v_fmac_f32_e32 v128, v120, v76
	v_fmac_f32_e32 v129, v119, v76
	v_fmac_f32_e32 v130, v118, v76
	v_fmac_f32_e32 v131, v117, v76
	v_fmac_f32_e32 v132, v116, v76
	v_fmac_f32_e32 v133, v115, v76
	v_fmac_f32_e32 v134, v114, v76
	v_fmac_f32_e32 v135, v113, v76
	v_fmac_f32_e32 v136, v112, v76
	v_fmac_f32_e32 v137, v111, v76
	v_fmac_f32_e32 v138, v110, v76
	v_fmac_f32_e32 v139, v109, v76
	v_fmac_f32_e32 v140, v108, v76
	v_fmac_f32_e32 v141, v107, v76
	v_fmac_f32_e32 v127, v122, v77
	v_fmac_f32_e32 v128, v121, v77
	v_fmac_f32_e32 v129, v120, v77
	v_fmac_f32_e32 v130, v119, v77
	v_fmac_f32_e32 v131, v118, v77
	v_fmac_f32_e32 v132, v117, v77
	v_fmac_f32_e32 v133, v116, v77
	v_fmac_f32_e32 v134, v115, v77
	v_fmac_f32_e32 v135, v114, v77
	v_fmac_f32_e32 v136, v113, v77
	v_fmac_f32_e32 v137, v112, v77
	v_fmac_f32_e32 v138, v111, v77
	v_fmac_f32_e32 v139, v110, v77
	v_fmac_f32_e32 v140, v109, v77
	v_fmac_f32_e32 v141, v108, v77
	v_fmac_f32_e32 v128, v122, v78
	v_fmac_f32_e32 v129, v121, v78
	v_fmac_f32_e32 v130, v120, v78
	v_fmac_f32_e32 v131, v119, v78
	v_fmac_f32_e32 v132, v118, v78
	v_fmac_f32_e32 v133, v117, v78
	v_fmac_f32_e32 v134, v116, v78
	v_fmac_f32_e32 v135, v115, v78
	v_fmac_f32_e32 v136, v114, v78
	v_fmac_f32_e32 v137, v113, v78
	v_fmac_f32_e32 v138, v112, v78
	v_fmac_f32_e32 v139, v111, v78
	v_fmac_f32_e32 v140, v110, v78
	v_fmac_f32_e32 v141, v109, v78
	v_fmac_f32_e32 v129, v122, v79
	v_fmac_f32_e32 v130, v121, v79
	v_fmac_f32_e32 v131, v120, v79
	v_fmac_f32_e32 v132, v119, v79
	v_fmac_f32_e32 v133, v118, v79
	v_fmac_f32_e32 v134, v117, v79
	v_fmac_f32_e32 v135, v116, v79
	v_fmac_f32_e32 v136, v115, v79
	v_fmac_f32_e32 v137, v114, v79
	v_fmac_f32_e32 v138, v113, v79
	v_fmac_f32_e32 v139, v112, v79
	v_fmac_f32_e32 v140, v111, v79
	v_fmac_f32_e32 v141, v110, v79
	v_fmac_f32_e32 v130, v122, v80
	v_fmac_f32_e32 v131, v121, v80
	v_fmac_f32_e32 v132, v120, v80
	v_fmac_f32_e32 v133, v119, v80
	v_fmac_f32_e32 v134, v118, v80
	v_fmac_f32_e32 v135, v117, v80
	v_fmac_f32_e32 v136, v116, v80
	v_fmac_f32_e32 v137, v115, v80
	v_fmac_f32_e32 v138, v114, v80
	v_fmac_f32_e32 v139, v113, v80
	v_fmac_f32_e32 v140, v112, v80
	v_fmac_f32_e32 v141, v111, v80
	v_fmac_f32_e32 v131, v122, v81
	v_fmac_f32_e32 v132, v121, v81
	v_fmac_f32_e32 v133, v120, v81
	v_fmac_f32_e32 v134, v119, v81
	v_fmac_f32_e32 v135, v118, v81
	v_fmac_f32_e32 v136, v117, v81
	v_fmac_f32_e32 v137, v116, v81
	v_fmac_f32_e32 v138, v115, v81
	v_fmac_f32_e32 v139, v114, v81
	v_fmac_f32_e32 v140, v113, v81
	v_fmac_f32_e32 v141, v112, v81
	v_fmac_f32_e32 v132, v122, v82
	v_fmac_f32_e32 v133, v121, v82
	v_fmac_f32_e32 v134, v120, v82
	v_fmac_f32_e32 v135, v119, v82
	v_fmac_f32_e32 v136, v118, v82
	v_fmac_f32_e32 v137, v117, v82
	v_fmac_f32_e32 v138, v116, v82
	v_fmac_f32_e32 v139, v115, v82
	v_fmac_f32_e32 v140, v114, v82
	v_fmac_f32_e32 v141, v113, v82
	v_fmac_f32_e32 v133, v122, v83
	v_fmac_f32_e32 v134, v121, v83
	v_fmac_f32_e32 v135, v120, v83
	v_fmac_f32_e32 v136, v119, v83
	v_fmac_f32_e32 v137, v118, v83
	v_fmac_f32_e32 v138, v117, v83
	v_fmac_f32_e32 v139, v116, v83
	v_fmac_f32_e32 v140, v115, v83
	v_fmac_f32_e32 v141, v114, v83
	v_fmac_f32_e32 v134, v122, v84
	v_fmac_f32_e32 v135, v121, v84
	v_fmac_f32_e32 v136, v120, v84
	v_fmac_f32_e32 v137, v119, v84
	v_fmac_f32_e32 v138, v118, v84
	v_fmac_f32_e32 v139, v117, v84
	v_fmac_f32_e32 v140, v116, v84
	v_fmac_f32_e32 v141, v115, v84
	v_fmac_f32_e32 v135, v122, v85
	v_fmac_f32_e32 v136, v121, v85
	v_fmac_f32_e32 v137, v120, v85
	v_fmac_f32_e32 v138, v119, v85
	v_fmac_f32_e32 v139, v118, v85
	v_fmac_f32_e32 v140, v117, v85
	v_fmac_f32_e32 v141, v116, v85
	v_fmac_f32_e32 v136, v122, v86
	v_fmac_f32_e32 v137, v121, v86
	v_fmac_f32_e32 v138, v120, v86
	v_fmac_f32_e32 v139, v119, v86
	v_fmac_f32_e32 v140, v118, v86
	v_fmac_f32_e32 v141, v117, v86
	v_fmac_f32_e32 v137, v122, v87
	v_fmac_f32_e32 v138, v121, v87
	v_fmac_f32_e32 v139, v120, v87
	v_fmac_f32_e32 v140, v119, v87
	v_fmac_f32_e32 v141, v118, v87
	v_fmac_f32_e32 v138, v122, v88
	v_fmac_f32_e32 v139, v121, v88
	v_fmac_f32_e32 v140, v120, v88
	v_fmac_f32_e32 v141, v119, v88
	v_fmac_f32_e32 v139, v122, v89
	v_fmac_f32_e32 v140, v121, v89
	v_fmac_f32_e32 v141, v120, v89
	v_fmac_f32_e32 v140, v122, v90
	v_fmac_f32_e32 v141, v121, v90
	v_fmac_f32_e32 v141, v122, v91
	ds_write_b32 v143, v126
	ds_write_b32 v143, v127 offset:2048
	ds_write_b32 v143, v128 offset:4096
	ds_write_b32 v143, v129 offset:6144
	ds_write_b32 v143, v130 offset:8192
	ds_write_b32 v143, v131 offset:10240
	ds_write_b32 v143, v132 offset:12288
	ds_write_b32 v143, v133 offset:14336
	ds_write_b32 v143, v134 offset:16384
	ds_write_b32 v143, v135 offset:18432
	ds_write_b32 v143, v136 offset:20480
	ds_write_b32 v143, v137 offset:22528
	ds_write_b32 v143, v138 offset:24576
	ds_write_b32 v143, v139 offset:26624
	ds_write_b32 v143, v140 offset:28672
	ds_write_b32 v143, v141 offset:30720
	s_waitcnt lgkmcnt(0)
	s_barrier
	ds_read_b128 v[46:49], v144
	ds_read_b128 v[50:53], v144 offset:16
	ds_read_b128 v[54:57], v144 offset:32
	ds_read_b128 v[58:61], v144 offset:48
	s_waitcnt lgkmcnt(0)
	v_add_f32_e32 v152, v46, v47
	v_mul_f32_e32 v153, v46, v46
	v_fmac_f32_e32 v153, v47, v47
	v_add_f32_e32 v152, v152, v48
	v_fmac_f32_e32 v153, v48, v48
	v_add_f32_e32 v152, v152, v49
	v_fmac_f32_e32 v153, v49, v49
	v_add_f32_e32 v152, v152, v50
	v_fmac_f32_e32 v153, v50, v50
	v_add_f32_e32 v152, v152, v51
	v_fmac_f32_e32 v153, v51, v51
	v_add_f32_e32 v152, v152, v52
	v_fmac_f32_e32 v153, v52, v52
	v_add_f32_e32 v152, v152, v53
	v_fmac_f32_e32 v153, v53, v53
	v_add_f32_e32 v152, v152, v54
	v_fmac_f32_e32 v153, v54, v54
	v_add_f32_e32 v152, v152, v55
	v_fmac_f32_e32 v153, v55, v55
	v_add_f32_e32 v152, v152, v56
	v_fmac_f32_e32 v153, v56, v56
	v_add_f32_e32 v152, v152, v57
	v_fmac_f32_e32 v153, v57, v57
	v_add_f32_e32 v152, v152, v58
	v_fmac_f32_e32 v153, v58, v58
	v_add_f32_e32 v152, v152, v59
	v_fmac_f32_e32 v153, v59, v59
	v_add_f32_e32 v152, v152, v60
	v_fmac_f32_e32 v153, v60, v60
	v_add_f32_e32 v152, v152, v61
	v_fmac_f32_e32 v153, v61, v61
	ds_bpermute_b32 v154, v146, v152
	ds_bpermute_b32 v155, v146, v153
	s_waitcnt lgkmcnt(1)
	v_add_f32_e32 v152, v152, v154
	s_waitcnt lgkmcnt(0)
	v_add_f32_e32 v153, v153, v155
	ds_bpermute_b32 v154, v147, v152
	ds_bpermute_b32 v155, v147, v153
	s_waitcnt lgkmcnt(1)
	v_add_f32_e32 v152, v152, v154
	s_waitcnt lgkmcnt(0)
	v_add_f32_e32 v153, v153, v155
	ds_bpermute_b32 v154, v148, v152
	ds_bpermute_b32 v155, v148, v153
	s_waitcnt lgkmcnt(1)
	v_add_f32_e32 v152, v152, v154
	s_waitcnt lgkmcnt(0)
	v_add_f32_e32 v153, v153, v155
	ds_bpermute_b32 v154, v149, v152
	ds_bpermute_b32 v155, v149, v153
	s_waitcnt lgkmcnt(1)
	v_add_f32_e32 v152, v152, v154
	s_waitcnt lgkmcnt(0)
	v_add_f32_e32 v153, v153, v155
	ds_bpermute_b32 v154, v150, v152
	ds_bpermute_b32 v155, v150, v153
	s_waitcnt lgkmcnt(1)
	v_add_f32_e32 v152, v152, v154
	s_waitcnt lgkmcnt(0)
	v_add_f32_e32 v153, v153, v155
	v_mul_f32_e32 v152, 0x3b000000, v152
	v_mul_f32_e32 v153, 0x3b000000, v153
	v_fma_f32 v153, -v152, v152, v153
	v_max_f32_e32 v153, 0, v153
	v_add_f32_e32 v153, v173, v153
	v_rsq_f32_e32 v153, v153
	s_mov_b32 s80, 1
	s_mov_b32 s81, 1
	s_mov_b64 exec, s[80:81]
	ds_write_b64 v145, v[152:153]
	s_mov_b64 exec, -1
	s_waitcnt lgkmcnt(0)
	s_barrier
	ds_read_b128 v[46:49], v151
	ds_read_b128 v[50:53], v151 offset:16
	ds_read_b128 v[54:57], v151 offset:32
	ds_read_b128 v[58:61], v151 offset:48
	ds_read_b128 v[62:65], v151 offset:64
	ds_read_b128 v[66:69], v151 offset:80
	ds_read_b128 v[70:73], v151 offset:96
	ds_read_b128 v[74:77], v151 offset:112
	s_lshl_b32 s80, s70, 16
	s_add_u32 s82, s46, s80
	s_addc_u32 s83, s47, 0
	s_waitcnt lgkmcnt(0)
	v_sub_f32_e32 v126, v126, v46
	v_sub_f32_e32 v127, v127, v48
	v_mul_f32_e32 v126, v126, v47
	v_mul_f32_e32 v127, v127, v49
	v_fma_f32 v126, v126, v124, v125
	v_fma_f32 v127, v127, v124, v125
	v_mul_f32_e32 v152, 0xbfb8aa3b, v126
	v_mul_f32_e32 v153, 0xbfb8aa3b, v127
	v_exp_f32_e32 v152, v152
	v_exp_f32_e32 v153, v153
	s_nop 0
	v_add_f32_e32 v152, 1.0, v152
	v_add_f32_e32 v153, 1.0, v153
	v_rcp_f32_e32 v152, v152
	v_rcp_f32_e32 v153, v153
	s_nop 0
	v_mul_f32_e32 v126, v126, v152
	v_mul_f32_e32 v127, v127, v153
	v_bfe_u32 v152, v126, 16, 1
	v_bfe_u32 v153, v127, 16, 1
	v_add3_u32 v126, v126, v152, s37
	v_add3_u32 v127, v127, v153, s37
	global_store_short_d16_hi v142, v126, s[82:83] offset:3072
	s_add_u32 s82, s82, 0x1000
	s_addc_u32 s83, s83, 0
	global_store_short_d16_hi v142, v127, s[82:83] offset:3072
	s_add_u32 s82, s82, 0x1000
	s_addc_u32 s83, s83, 0
	v_sub_f32_e32 v128, v128, v50
	v_sub_f32_e32 v129, v129, v52
	v_mul_f32_e32 v128, v128, v51
	v_mul_f32_e32 v129, v129, v53
	v_fma_f32 v128, v128, v124, v125
	v_fma_f32 v129, v129, v124, v125
	v_mul_f32_e32 v152, 0xbfb8aa3b, v128
	v_mul_f32_e32 v153, 0xbfb8aa3b, v129
	v_exp_f32_e32 v152, v152
	v_exp_f32_e32 v153, v153
	s_nop 0
	v_add_f32_e32 v152, 1.0, v152
	v_add_f32_e32 v153, 1.0, v153
	v_rcp_f32_e32 v152, v152
	v_rcp_f32_e32 v153, v153
	s_nop 0
	v_mul_f32_e32 v128, v128, v152
	v_mul_f32_e32 v129, v129, v153
	v_bfe_u32 v152, v128, 16, 1
	v_bfe_u32 v153, v129, 16, 1
	v_add3_u32 v128, v128, v152, s37
	v_add3_u32 v129, v129, v153, s37
	global_store_short_d16_hi v142, v128, s[82:83] offset:3072
	s_add_u32 s82, s82, 0x1000
	s_addc_u32 s83, s83, 0
	global_store_short_d16_hi v142, v129, s[82:83] offset:3072
	s_add_u32 s82, s82, 0x1000
	s_addc_u32 s83, s83, 0
	v_sub_f32_e32 v130, v130, v54
	v_sub_f32_e32 v131, v131, v56
	v_mul_f32_e32 v130, v130, v55
	v_mul_f32_e32 v131, v131, v57
	v_fma_f32 v130, v130, v124, v125
	v_fma_f32 v131, v131, v124, v125
	v_mul_f32_e32 v152, 0xbfb8aa3b, v130
	v_mul_f32_e32 v153, 0xbfb8aa3b, v131
	v_exp_f32_e32 v152, v152
	v_exp_f32_e32 v153, v153
	s_nop 0
	v_add_f32_e32 v152, 1.0, v152
	v_add_f32_e32 v153, 1.0, v153
	v_rcp_f32_e32 v152, v152
	v_rcp_f32_e32 v153, v153
	s_nop 0
	v_mul_f32_e32 v130, v130, v152
	v_mul_f32_e32 v131, v131, v153
	v_bfe_u32 v152, v130, 16, 1
	v_bfe_u32 v153, v131, 16, 1
	v_add3_u32 v130, v130, v152, s37
	v_add3_u32 v131, v131, v153, s37
	global_store_short_d16_hi v142, v130, s[82:83] offset:3072
	s_add_u32 s82, s82, 0x1000
	s_addc_u32 s83, s83, 0
	global_store_short_d16_hi v142, v131, s[82:83] offset:3072
	s_add_u32 s82, s82, 0x1000
	s_addc_u32 s83, s83, 0
	v_sub_f32_e32 v132, v132, v58
	v_sub_f32_e32 v133, v133, v60
	v_mul_f32_e32 v132, v132, v59
	v_mul_f32_e32 v133, v133, v61
	v_fma_f32 v132, v132, v124, v125
	v_fma_f32 v133, v133, v124, v125
	v_mul_f32_e32 v152, 0xbfb8aa3b, v132
	v_mul_f32_e32 v153, 0xbfb8aa3b, v133
	v_exp_f32_e32 v152, v152
	v_exp_f32_e32 v153, v153
	s_nop 0
	v_add_f32_e32 v152, 1.0, v152
	v_add_f32_e32 v153, 1.0, v153
	v_rcp_f32_e32 v152, v152
	v_rcp_f32_e32 v153, v153
	s_nop 0
	v_mul_f32_e32 v132, v132, v152
	v_mul_f32_e32 v133, v133, v153
	v_bfe_u32 v152, v132, 16, 1
	v_bfe_u32 v153, v133, 16, 1
	v_add3_u32 v132, v132, v152, s37
	v_add3_u32 v133, v133, v153, s37
	global_store_short_d16_hi v142, v132, s[82:83] offset:3072
	s_add_u32 s82, s82, 0x1000
	s_addc_u32 s83, s83, 0
	global_store_short_d16_hi v142, v133, s[82:83] offset:3072
	s_add_u32 s82, s82, 0x1000
	s_addc_u32 s83, s83, 0
	v_sub_f32_e32 v134, v134, v62
	v_sub_f32_e32 v135, v135, v64
	v_mul_f32_e32 v134, v134, v63
	v_mul_f32_e32 v135, v135, v65
	v_fma_f32 v134, v134, v124, v125
	v_fma_f32 v135, v135, v124, v125
	v_mul_f32_e32 v152, 0xbfb8aa3b, v134
	v_mul_f32_e32 v153, 0xbfb8aa3b, v135
	v_exp_f32_e32 v152, v152
	v_exp_f32_e32 v153, v153
	s_nop 0
	v_add_f32_e32 v152, 1.0, v152
	v_add_f32_e32 v153, 1.0, v153
	v_rcp_f32_e32 v152, v152
	v_rcp_f32_e32 v153, v153
	s_nop 0
	v_mul_f32_e32 v134, v134, v152
	v_mul_f32_e32 v135, v135, v153
	v_bfe_u32 v152, v134, 16, 1
	v_bfe_u32 v153, v135, 16, 1
	v_add3_u32 v134, v134, v152, s37
	v_add3_u32 v135, v135, v153, s37
	global_store_short_d16_hi v142, v134, s[82:83] offset:3072
	s_add_u32 s82, s82, 0x1000
	s_addc_u32 s83, s83, 0
	global_store_short_d16_hi v142, v135, s[82:83] offset:3072
	s_add_u32 s82, s82, 0x1000
	s_addc_u32 s83, s83, 0
	v_sub_f32_e32 v136, v136, v66
	v_sub_f32_e32 v137, v137, v68
	v_mul_f32_e32 v136, v136, v67
	v_mul_f32_e32 v137, v137, v69
	v_fma_f32 v136, v136, v124, v125
	v_fma_f32 v137, v137, v124, v125
	v_mul_f32_e32 v152, 0xbfb8aa3b, v136
	v_mul_f32_e32 v153, 0xbfb8aa3b, v137
	v_exp_f32_e32 v152, v152
	v_exp_f32_e32 v153, v153
	s_nop 0
	v_add_f32_e32 v152, 1.0, v152
	v_add_f32_e32 v153, 1.0, v153
	v_rcp_f32_e32 v152, v152
	v_rcp_f32_e32 v153, v153
	s_nop 0
	v_mul_f32_e32 v136, v136, v152
	v_mul_f32_e32 v137, v137, v153
	v_bfe_u32 v152, v136, 16, 1
	v_bfe_u32 v153, v137, 16, 1
	v_add3_u32 v136, v136, v152, s37
	v_add3_u32 v137, v137, v153, s37
	global_store_short_d16_hi v142, v136, s[82:83] offset:3072
	s_add_u32 s82, s82, 0x1000
	s_addc_u32 s83, s83, 0
	global_store_short_d16_hi v142, v137, s[82:83] offset:3072
	s_add_u32 s82, s82, 0x1000
	s_addc_u32 s83, s83, 0
	v_sub_f32_e32 v138, v138, v70
	v_sub_f32_e32 v139, v139, v72
	v_mul_f32_e32 v138, v138, v71
	v_mul_f32_e32 v139, v139, v73
	v_fma_f32 v138, v138, v124, v125
	v_fma_f32 v139, v139, v124, v125
	v_mul_f32_e32 v152, 0xbfb8aa3b, v138
	v_mul_f32_e32 v153, 0xbfb8aa3b, v139
	v_exp_f32_e32 v152, v152
	v_exp_f32_e32 v153, v153
	s_nop 0
	v_add_f32_e32 v152, 1.0, v152
	v_add_f32_e32 v153, 1.0, v153
	v_rcp_f32_e32 v152, v152
	v_rcp_f32_e32 v153, v153
	s_nop 0
	v_mul_f32_e32 v138, v138, v152
	v_mul_f32_e32 v139, v139, v153
	v_bfe_u32 v152, v138, 16, 1
	v_bfe_u32 v153, v139, 16, 1
	v_add3_u32 v138, v138, v152, s37
	v_add3_u32 v139, v139, v153, s37
	global_store_short_d16_hi v142, v138, s[82:83] offset:3072
	s_add_u32 s82, s82, 0x1000
	s_addc_u32 s83, s83, 0
	global_store_short_d16_hi v142, v139, s[82:83] offset:3072
	s_add_u32 s82, s82, 0x1000
	s_addc_u32 s83, s83, 0
	v_sub_f32_e32 v140, v140, v74
	v_sub_f32_e32 v141, v141, v76
	v_mul_f32_e32 v140, v140, v75
	v_mul_f32_e32 v141, v141, v77
	v_fma_f32 v140, v140, v124, v125
	v_fma_f32 v141, v141, v124, v125
	v_mul_f32_e32 v152, 0xbfb8aa3b, v140
	v_mul_f32_e32 v153, 0xbfb8aa3b, v141
	v_exp_f32_e32 v152, v152
	v_exp_f32_e32 v153, v153
	s_nop 0
	v_add_f32_e32 v152, 1.0, v152
	v_add_f32_e32 v153, 1.0, v153
	v_rcp_f32_e32 v152, v152
	v_rcp_f32_e32 v153, v153
	s_nop 0
	v_mul_f32_e32 v140, v140, v152
	v_mul_f32_e32 v141, v141, v153
	v_bfe_u32 v152, v140, 16, 1
	v_bfe_u32 v153, v141, 16, 1
	v_add3_u32 v140, v140, v152, s37
	v_add3_u32 v141, v141, v153, s37
	global_store_short_d16_hi v142, v140, s[82:83] offset:3072
	s_add_u32 s82, s82, 0x1000
	s_addc_u32 s83, s83, 0
	global_store_short_d16_hi v142, v141, s[82:83] offset:3072
	s_add_u32 s82, s82, 0x1000
	s_addc_u32 s83, s83, 0
	s_add_i32 s70, s70, s97
	s_cmp_lt_i32 s70, s71
	s_cbranch_scc1 .Lconv_loop
	s_waitcnt vmcnt(0)
	s_waitcnt lgkmcnt(0)
	s_barrier
	s_branch .LBB0_705
